# static s_setprio 1 for the younger wave half also during the attention+GLA0 and GLA1 phases (reset before each grid barrier)
# speedup vs baseline: 1.0175x; 1.0012x over previous
.LBB0_511:
	s_or_b64 exec, exec, s[4:5]
	s_waitcnt lgkmcnt(0)
	s_barrier
	v_readfirstlane_b32 s92, v240
	s_cmpk_lt_u32 s92, 0x100
	s_cbranch_scc1 .Lprio_a
	s_setprio 1
.Lprio_a:
	s_load_dwordx2 s[4:5], s[0:1], 0xa8
	v_mov_b32_e32 v187, v240
	s_waitcnt lgkmcnt(0)
	v_mov_b32_e32 v0, s5
	v_mov_b32_e32 v1, s4
	s_nop 0
	v_readfirstlane_b32 s42, v0
	v_mov_b32_e32 v0, s2
	v_readfirstlane_b32 s41, v1
	v_readfirstlane_b32 s33, v0
	v_mov_b32_e32 v0, s24
	s_cmpk_gt_i32 s33, 0x2ff
	v_readfirstlane_b32 s40, v0
	s_cbranch_scc1 .LBB0_572
	s_add_u32 s8, s41, 0x9800000
	s_addc_u32 s9, s42, 0
	s_add_u32 s10, s41, 0x3790000
	s_addc_u32 s11, s42, 0
	s_add_u32 s12, s41, 0xc800000
	s_addc_u32 s13, s42, 0
	s_add_u32 s14, s41, 0xd400000
	s_addc_u32 s15, s42, 0
	s_add_u32 s16, s41, 0x17600000
	s_addc_u32 s17, s42, 0
	s_movk_i32 s43, 0x800
	s_mov_b32 s19, 0
	v_mov_b32_e32 v1, 0
	s_movk_i32 s44, 0x100
	s_movk_i32 s45, 0x90
	s_movk_i32 s46, 0x2400
	s_add_i32 s47, 0, 0x1200
	s_mov_b32 s48, 0xf149f2ca
	s_movk_i32 s49, 0xffe0
	v_mov_b32_e32 v189, 0xf149f2ca
	v_mov_b32_e32 v190, 0x160
	s_mov_b32 s50, s33
	s_branch .LBB0_514

.LBB0_591:
	s_setprio 0
	s_load_dwordx2 s[4:5], s[0:1], 0xa8
	s_waitcnt vmcnt(0) lgkmcnt(0)
	v_mov_b32_e32 v0, s5
	v_mov_b32_e32 v1, s4
	s_waitcnt vmcnt(0)
	s_nop 0
	v_readfirstlane_b32 s6, v1
	v_readfirstlane_b32 s7, v0
	s_barrier
	s_and_saveexec_b64 s[4:5], s[22:23]
	s_cbranch_execz .LBB0_643
	s_add_i32 s9, 0, 0x24800
	v_mov_b32_e32 v0, s9
	s_getreg_b32 s8, hwreg(HW_REG_XCC_ID, 0, 4)
	s_waitcnt vmcnt(0) expcnt(0) lgkmcnt(0)
	ds_read_b32 v2, v0
	s_add_i32 s9, 0, 0x24804
	v_mov_b32_e32 v0, s9
	ds_read_b32 v0, v0
	s_and_b32 s33, s8, 15
	s_waitcnt lgkmcnt(1)
	v_cmp_ne_u32_e32 vcc, 0, v2
	s_cbranch_vccnz .LBB0_607
	s_mul_i32 s8, s25, s3
	s_waitcnt lgkmcnt(0)
	v_mul_lo_u32 v0, s8, v242
	s_add_u32 s8, s6, 0x37a9200
	s_addc_u32 s9, s7, 0
	s_add_u32 s10, s6, 0x37a9400
	s_addc_u32 s11, s7, 0
	s_add_u32 s12, s6, 0x37a9500
	s_addc_u32 s13, s7, 0
	s_add_u32 s14, s6, 0x37a9600
	s_addc_u32 s15, s7, 0
	s_add_u32 s16, s6, 0x37a9700
	s_addc_u32 s17, s7, 0
	s_add_u32 s18, s6, 0x37a9800
	s_addc_u32 s19, s7, 0
	s_add_u32 s20, s6, 0x37a9900
	s_addc_u32 s21, s7, 0
	s_add_u32 s26, s6, 0x37a9a00
	s_addc_u32 s27, s7, 0
	s_add_u32 s28, s6, 0x37a9b00
	s_addc_u32 s29, s7, 0
	s_add_u32 s30, s6, 0x37a9c00
	s_addc_u32 s31, s7, 0
	s_add_u32 s34, s6, 0x37a9d00
	s_addc_u32 s35, s7, 0
	s_add_u32 s36, s6, 0x37a9e00
	s_addc_u32 s37, s7, 0
	s_add_u32 s38, s6, 0x37a9f00
	s_addc_u32 s39, s7, 0
	s_add_u32 s40, s6, 0x37aa000
	s_addc_u32 s41, s7, 0
	s_add_u32 s42, s6, 0x37aa100
	s_addc_u32 s43, s7, 0
	s_add_u32 s44, s6, 0x37aa200
	s_addc_u32 s45, s7, 0
	s_add_u32 s46, s6, 0x37aa300
	s_addc_u32 s47, s7, 0
	s_mov_b32 s54, 1
	v_mov_b32_e32 v17, 0
	s_branch .LBB0_595

.Lprio_b:
	s_load_dwordx4 s[8:11], s[0:1], 0xa0
	v_mov_b32_e32 v172, v240
	v_mov_b32_e32 v3, 0x100
	v_mov_b32_e32 v149, 0
	s_movk_i32 s30, 0x1000
	s_waitcnt lgkmcnt(0)
	v_mov_b32_e32 v0, s10
	v_mov_b32_e32 v1, s11
	v_mov_b32_e32 v16, s24
	v_readfirstlane_b32 s6, v0
	v_mov_b32_e32 v0, s2
	v_readfirstlane_b32 s7, v1
	v_ashrrev_i32_e32 v1, 2, v172
	v_readfirstlane_b32 s28, v0
	s_and_b32 s16, s28, 1
	v_and_b32_e32 v1, 0xffffffc0, v1
	v_lshrrev_b32_e32 v2, 1, v172
	v_and_b32_e32 v0, 31, v172
	v_lshl_add_u32 v1, s16, 7, v1
	v_and_b32_e32 v2, 32, v2
	v_or3_b32 v10, v2, v0, v1
	v_and_b32_e32 v0, 0x80, v172
	s_add_u32 s12, s6, 0x3790000
	v_mov_b32_e32 v2, 0x4500
	v_cmp_eq_u32_e32 vcc, 0, v0
	s_addc_u32 s13, s7, 0
	v_ashrrev_i32_e32 v11, 31, v10
	v_cndmask_b32_e32 v148, v2, v3, vcc
	v_lshl_add_u64 v[2:3], s[12:13], 0, v[148:149]
	v_lshlrev_b32_e32 v0, 8, v172
	v_lshl_add_u64 v[2:3], v[10:11], 2, v[2:3]
	v_and_b32_e32 v148, 0x2000, v0
	v_lshl_add_u64 v[12:13], v[2:3], 0, v[148:149]
	v_add_co_u32_e64 v14, s[4:5], s30, v12
	v_mov_b32_e32 v0, 0x2140
	s_nop 0
	v_addc_co_u32_e64 v15, s[4:5], 0, v13, s[4:5]
	global_load_dword v2, v[12:13], off
	global_load_dword v3, v[12:13], off offset:1024
	global_load_dword v4, v[12:13], off offset:2048
	global_load_dword v5, v[12:13], off offset:3072
	global_load_dword v6, v[14:15], off
	global_load_dword v7, v[14:15], off offset:1024
	global_load_dword v8, v[14:15], off offset:2048
	global_load_dword v9, v[14:15], off offset:3072
	v_mov_b32_e32 v11, 0x1040
	v_cndmask_b32_e32 v0, v0, v11, vcc
	v_add_u32_e32 v10, v10, v0
	v_ashrrev_i32_e32 v11, 31, v10
	v_lshl_add_u64 v[10:11], v[10:11], 2, s[12:13]
	global_load_dword v0, v[10:11], off
	v_mov_b32_e32 v10, s9
	v_mov_b32_e32 v11, s8
	v_readfirstlane_b32 s31, v16
	s_cmpk_lt_i32 s28, 0x600
	v_readfirstlane_b32 s8, v11
	v_readfirstlane_b32 s9, v10
	s_cbranch_scc0 .LBB0_726
	s_lshl_b32 s4, s28, 5
	s_and_b32 s17, s4, 0xffffffc0
	v_lshrrev_b32_e32 v11, 2, v172
	s_add_u32 s10, s6, 0xe000000
	s_addc_u32 s11, s7, 0
	v_and_or_b32 v12, v11, 48, s17
	s_add_u32 s12, s6, 0xf800000
	v_and_or_b32 v10, v172, 63, v1
	v_ashrrev_i32_e32 v13, 31, v12
	s_addc_u32 s13, s7, 0
	v_lshlrev_b64 v[12:13], 9, v[12:13]
	v_ashrrev_i32_e32 v11, 31, v10
	v_lshl_add_u64 v[14:15], s[12:13], 0, v[12:13]
	v_lshlrev_b64 v[10:11], 1, v[10:11]
	v_lshl_add_u64 v[14:15], v[14:15], 0, v[10:11]
	v_lshl_add_u64 v[12:13], s[10:11], 0, v[12:13]
	v_lshl_add_u64 v[10:11], v[12:13], 0, v[10:11]
	v_add_co_u32_e32 v12, vcc, s30, v14
	global_load_ushort v1, v[14:15], off
	global_load_ushort v16, v[14:15], off offset:512
	global_load_ushort v17, v[14:15], off offset:1024
	global_load_ushort v18, v[14:15], off offset:1536
	global_load_ushort v19, v[14:15], off offset:2048
	global_load_ushort v20, v[14:15], off offset:2560
	global_load_ushort v21, v[14:15], off offset:3072
	global_load_ushort v22, v[14:15], off offset:3584
	global_load_ushort v23, v[10:11], off
	global_load_ushort v24, v[10:11], off offset:512
	global_load_ushort v25, v[10:11], off offset:1024
	global_load_ushort v26, v[10:11], off offset:1536
	global_load_ushort v27, v[10:11], off offset:2048
	global_load_ushort v28, v[10:11], off offset:2560
	global_load_ushort v29, v[10:11], off offset:3072
	global_load_ushort v30, v[10:11], off offset:3584
	v_addc_co_u32_e32 v13, vcc, 0, v15, vcc
	v_add_co_u32_e32 v10, vcc, s30, v10
	s_add_u32 s33, s6, 0x11000000
	s_nop 0
	v_addc_co_u32_e32 v11, vcc, 0, v11, vcc
	global_load_ushort v31, v[12:13], off
	global_load_ushort v32, v[12:13], off offset:512
	global_load_ushort v33, v[12:13], off offset:1024
	global_load_ushort v34, v[12:13], off offset:1536
	global_load_ushort v35, v[12:13], off offset:2048
	global_load_ushort v36, v[12:13], off offset:2560
	global_load_ushort v37, v[12:13], off offset:3072
	global_load_ushort v38, v[12:13], off offset:3584
	global_load_ushort v39, v[10:11], off
	global_load_ushort v40, v[10:11], off offset:512
	global_load_ushort v41, v[10:11], off offset:1024
	global_load_ushort v42, v[10:11], off offset:1536
	global_load_ushort v43, v[10:11], off offset:2048
	global_load_ushort v44, v[10:11], off offset:2560
	global_load_ushort v45, v[10:11], off offset:3072
	global_load_ushort v46, v[10:11], off offset:3584
	v_ashrrev_i32_e32 v10, 3, v172
	s_addc_u32 s34, s7, 0
	v_add_u32_e32 v10, s17, v10
	s_add_u32 s14, s6, 0x17000000
	v_ashrrev_i32_e32 v11, 31, v10
	s_addc_u32 s15, s7, 0
	v_lshlrev_b64 v[10:11], 7, v[10:11]
	v_lshlrev_b32_e32 v12, 4, v172
	s_lshl_b32 s4, s16, 9
	v_ashrrev_i32_e32 v14, 5, v172
	v_lshl_add_u64 v[10:11], s[14:15], 0, v[10:11]
	v_and_b32_e32 v148, 0x70, v12
	s_add_u32 s4, s33, s4
	v_add_u32_e32 v14, s17, v14
	v_lshl_add_u64 v[10:11], v[10:11], 0, v[148:149]
	s_addc_u32 s5, s34, 0
	v_and_b32_e32 v148, 0x1f0, v12
	v_ashrrev_i32_e32 v15, 31, v14
	v_lshl_add_u64 v[12:13], s[4:5], 0, v[148:149]
	v_lshlrev_b64 v[14:15], 10, v[14:15]
	v_lshl_add_u64 v[14:15], v[12:13], 0, v[14:15]
	global_load_dwordx4 v[72:75], v[10:11], off
	global_load_dwordx4 v[76:79], v[14:15], off
	v_add_u32_e32 v10, 0x200, v172
	v_ashrrev_i32_e32 v10, 5, v10
	v_add_u32_e32 v14, 0x400, v172
	v_add_u32_e32 v10, s17, v10
	v_ashrrev_i32_e32 v14, 5, v14
	v_ashrrev_i32_e32 v11, 31, v10
	v_add_u32_e32 v14, s17, v14
	v_lshlrev_b64 v[10:11], 10, v[10:11]
	v_ashrrev_i32_e32 v15, 31, v14
	v_lshl_add_u64 v[10:11], v[12:13], 0, v[10:11]
	v_lshlrev_b64 v[14:15], 10, v[14:15]
	v_lshl_add_u64 v[14:15], v[12:13], 0, v[14:15]
	global_load_dwordx4 v[80:83], v[10:11], off
	global_load_dwordx4 v[84:87], v[14:15], off
	v_add_u32_e32 v10, 0x600, v172
	v_ashrrev_i32_e32 v10, 5, v10
	v_add_u32_e32 v10, s17, v10
	v_ashrrev_i32_e32 v11, 31, v10
	v_lshlrev_b64 v[10:11], 10, v[10:11]
	v_lshl_add_u64 v[10:11], v[12:13], 0, v[10:11]
	global_load_dwordx4 v[88:91], v[10:11], off
	s_mov_b32 s35, 0x5040100
	s_waitcnt vmcnt(44)
	v_cvt_pk_bf16_f32 v10, v3, 0
	v_lshlrev_b32_e32 v11, 16, v10
	s_waitcnt vmcnt(42)
	v_cvt_pk_bf16_f32 v12, v5, 0
	v_lshlrev_b32_e32 v13, 16, v12
	s_waitcnt vmcnt(40)
	v_cvt_pk_bf16_f32 v14, v7, 0
	v_lshlrev_b32_e32 v15, 16, v14
	s_add_u32 s16, s6, 0x14000000
	s_addc_u32 s17, s7, 0
	s_add_u32 s18, s6, 0x3798900
	v_cvt_pk_bf16_f32 v64, v2, v3
	v_cvt_pk_bf16_f32 v65, v4, v5
	v_cvt_pk_bf16_f32 v66, v6, v7
	s_waitcnt vmcnt(38)
	v_cvt_pk_bf16_f32 v67, v8, v9
	s_addc_u32 s19, s7, 0
	s_lshl_b32 s36, s28, 1
	s_lshl_b32 s37, s31, 1
	s_movk_i32 s38, 0x220
	s_movk_i32 s39, 0x90
	v_mov_b32_e32 v173, 0x358637bd
	s_mov_b32 s40, 0x800000
	s_mov_b64 s[20:21], 0x17600400
	s_waitcnt vmcnt(28)
	v_perm_b32 v175, v23, v1, s35
	v_cvt_pk_bf16_f32 v1, v2, 0
	v_lshlrev_b32_e32 v10, 16, v1
	v_cvt_pk_bf16_f32 v1, v4, 0
	v_lshlrev_b32_e32 v12, 16, v1
	v_cvt_pk_bf16_f32 v1, v6, 0
	s_waitcnt vmcnt(27)
	v_perm_b32 v176, v24, v16, s35
	v_lshlrev_b32_e32 v14, 16, v1
	v_cvt_pk_bf16_f32 v1, v8, 0
	v_cvt_pk_bf16_f32 v16, v9, 0
	s_waitcnt vmcnt(26)
	v_perm_b32 v177, v25, v17, s35
	v_lshlrev_b32_e32 v17, 16, v16
	v_lshlrev_b32_e32 v16, 16, v1
	v_pk_add_f32 v[10:11], v[2:3], v[10:11] neg_lo:[0,1] neg_hi:[0,1]
	v_pk_add_f32 v[12:13], v[4:5], v[12:13] neg_lo:[0,1] neg_hi:[0,1]
	v_pk_add_f32 v[14:15], v[6:7], v[14:15] neg_lo:[0,1] neg_hi:[0,1]
	v_pk_add_f32 v[16:17], v[8:9], v[16:17] neg_lo:[0,1] neg_hi:[0,1]
	s_waitcnt vmcnt(25)
	v_perm_b32 v178, v26, v18, s35
	s_waitcnt vmcnt(24)
	v_perm_b32 v179, v27, v19, s35
	s_waitcnt vmcnt(23)
	v_perm_b32 v180, v28, v20, s35
	s_waitcnt vmcnt(22)
	v_perm_b32 v181, v29, v21, s35
	s_waitcnt vmcnt(21)
	v_perm_b32 v182, v30, v22, s35
	s_waitcnt vmcnt(12)
	v_perm_b32 v183, v39, v31, s35
	s_waitcnt vmcnt(11)
	v_perm_b32 v184, v40, v32, s35
	s_waitcnt vmcnt(10)
	v_perm_b32 v185, v41, v33, s35
	s_waitcnt vmcnt(9)
	v_perm_b32 v186, v42, v34, s35
	s_waitcnt vmcnt(8)
	v_perm_b32 v187, v43, v35, s35
	s_waitcnt vmcnt(7)
	v_perm_b32 v188, v44, v36, s35
	s_waitcnt vmcnt(6)
	v_perm_b32 v189, v45, v37, s35
	s_waitcnt vmcnt(5)
	v_perm_b32 v190, v46, v38, s35
	v_cvt_pk_bf16_f32 v68, v10, v11
	v_cvt_pk_bf16_f32 v69, v12, v13
	v_cvt_pk_bf16_f32 v70, v14, v15
	v_cvt_pk_bf16_f32 v71, v16, v17
	v_mov_b32_e32 v1, v0
	v_mov_b32_e32 v2, v0
	v_mov_b32_e32 v3, v0
	v_mov_b32_e32 v4, v0
	v_mov_b32_e32 v5, v0
	v_mov_b32_e32 v6, v0
	v_mov_b32_e32 v7, v0
	v_mov_b32_e32 v8, v0
	v_mov_b32_e32 v9, v0
	v_mov_b32_e32 v10, v0
	v_mov_b32_e32 v11, v0
	v_mov_b32_e32 v12, v0
	v_mov_b32_e32 v13, v0
	v_mov_b32_e32 v14, v0
	v_mov_b32_e32 v15, v0
	s_mov_b32 s41, 0x17600000
	v_mov_b32_e32 v174, 0x1200
	s_branch .LBB0_701

.LBB0_726:
	s_setprio 0
	s_waitcnt vmcnt(0) lgkmcnt(0)
	v_mov_b32_e32 v0, s10
	v_mov_b32_e32 v1, s11
	s_waitcnt vmcnt(0)
	s_nop 0
	v_readfirstlane_b32 s6, v0
	v_readfirstlane_b32 s7, v1
	s_barrier
	s_and_saveexec_b64 s[4:5], s[22:23]
	s_cbranch_execz .LBB0_778
	s_add_i32 s9, 0, 0x24800
	v_mov_b32_e32 v0, s9
	s_getreg_b32 s8, hwreg(HW_REG_XCC_ID, 0, 4)
	s_waitcnt vmcnt(0) expcnt(0) lgkmcnt(0)
	ds_read_b32 v2, v0
	s_add_i32 s9, 0, 0x24804
	v_mov_b32_e32 v0, s9
	ds_read_b32 v0, v0
	s_and_b32 s33, s8, 15
	s_waitcnt lgkmcnt(1)
	v_cmp_ne_u32_e32 vcc, 0, v2
	s_cbranch_vccnz .LBB0_742
	s_mul_i32 s8, s25, s3
	s_waitcnt lgkmcnt(0)
	v_mul_lo_u32 v0, s8, v242
	s_add_u32 s8, s6, 0x37a9200
	s_addc_u32 s9, s7, 0
	s_add_u32 s10, s6, 0x37a9400
	s_addc_u32 s11, s7, 0
	s_add_u32 s12, s6, 0x37a9500
	s_addc_u32 s13, s7, 0
	s_add_u32 s14, s6, 0x37a9600
	s_addc_u32 s15, s7, 0
	s_add_u32 s16, s6, 0x37a9700
	s_addc_u32 s17, s7, 0
	s_add_u32 s18, s6, 0x37a9800
	s_addc_u32 s19, s7, 0
	s_add_u32 s20, s6, 0x37a9900
	s_addc_u32 s21, s7, 0
	s_add_u32 s26, s6, 0x37a9a00
	s_addc_u32 s27, s7, 0
	s_add_u32 s28, s6, 0x37a9b00
	s_addc_u32 s29, s7, 0
	s_add_u32 s30, s6, 0x37a9c00
	s_addc_u32 s31, s7, 0
	s_add_u32 s34, s6, 0x37a9d00
	s_addc_u32 s35, s7, 0
	s_add_u32 s36, s6, 0x37a9e00
	s_addc_u32 s37, s7, 0
	s_add_u32 s38, s6, 0x37a9f00
	s_addc_u32 s39, s7, 0
	s_add_u32 s40, s6, 0x37aa000
	s_addc_u32 s41, s7, 0
	s_add_u32 s42, s6, 0x37aa100
	s_addc_u32 s43, s7, 0
	s_add_u32 s44, s6, 0x37aa200
	s_addc_u32 s45, s7, 0
	s_add_u32 s46, s6, 0x37aa300
	s_addc_u32 s47, s7, 0
	s_mov_b32 s54, 1
	v_mov_b32_e32 v17, 0
	s_branch .LBB0_730

	.amdhsa_kernel _Z9hymba_fwd6Params
		.amdhsa_group_segment_fixed_size 0
		.amdhsa_private_segment_fixed_size 0
		.amdhsa_kernarg_size 432
		.amdhsa_user_sgpr_count 2
		.amdhsa_user_sgpr_dispatch_ptr 0
		.amdhsa_user_sgpr_queue_ptr 0
		.amdhsa_user_sgpr_kernarg_segment_ptr 1
		.amdhsa_user_sgpr_dispatch_id 0
		.amdhsa_user_sgpr_kernarg_preload_length 0
		.amdhsa_user_sgpr_kernarg_preload_offset 0
		.amdhsa_user_sgpr_private_segment_size 0
		.amdhsa_uses_dynamic_stack 0
		.amdhsa_enable_private_segment 0
		.amdhsa_system_sgpr_workgroup_id_x 1
		.amdhsa_system_sgpr_workgroup_id_y 0
		.amdhsa_system_sgpr_workgroup_id_z 0
		.amdhsa_system_sgpr_workgroup_info 0
		.amdhsa_system_vgpr_workitem_id 2
		.amdhsa_next_free_vgpr 248
		.amdhsa_next_free_sgpr 93
		.amdhsa_accum_offset 248
		.amdhsa_reserve_vcc 1
		.amdhsa_float_round_mode_32 0
		.amdhsa_float_round_mode_16_64 0
		.amdhsa_float_denorm_mode_32 3
		.amdhsa_float_denorm_mode_16_64 3
		.amdhsa_dx10_clamp 1
		.amdhsa_ieee_mode 1
		.amdhsa_fp16_overflow 0
		.amdhsa_tg_split 0
		.amdhsa_exception_fp_ieee_invalid_op 0
		.amdhsa_exception_fp_denorm_src 0
		.amdhsa_exception_fp_ieee_div_zero 0
		.amdhsa_exception_fp_ieee_overflow 0
		.amdhsa_exception_fp_ieee_underflow 0
		.amdhsa_exception_fp_ieee_inexact 0
		.amdhsa_exception_int_div_zero 0
	.end_amdhsa_kernel

amdhsa.kernels:
  - .agpr_count:     0
    .args:
      - .offset:         0
        .size:           176
        .value_kind:     by_value
      - .offset:         176
        .size:           4
        .value_kind:     hidden_block_count_x
      - .offset:         180
        .size:           4
        .value_kind:     hidden_block_count_y
      - .offset:         184
        .size:           4
        .value_kind:     hidden_block_count_z
      - .offset:         188
        .size:           2
        .value_kind:     hidden_group_size_x
      - .offset:         190
        .size:           2
        .value_kind:     hidden_group_size_y
      - .offset:         192
        .size:           2
        .value_kind:     hidden_group_size_z
      - .offset:         194
        .size:           2
        .value_kind:     hidden_remainder_x
      - .offset:         196
        .size:           2
        .value_kind:     hidden_remainder_y
      - .offset:         198
        .size:           2
        .value_kind:     hidden_remainder_z
      - .offset:         216
        .size:           8
        .value_kind:     hidden_global_offset_x
      - .offset:         224
        .size:           8
        .value_kind:     hidden_global_offset_y
      - .offset:         232
        .size:           8
        .value_kind:     hidden_global_offset_z
      - .offset:         240
        .size:           2
        .value_kind:     hidden_grid_dims
      - .offset:         264
        .size:           8
        .value_kind:     hidden_multigrid_sync_arg
      - .offset:         296
        .size:           4
        .value_kind:     hidden_dynamic_lds_size
    .group_segment_fixed_size: 0
    .kernarg_segment_align: 8
    .kernarg_segment_size: 432
    .language:       OpenCL C
    .language_version:
      - 2
      - 0
    .max_flat_workgroup_size: 512
    .name:           _Z9hymba_fwd6Params
    .private_segment_fixed_size: 0
    .sgpr_count:     99
    .sgpr_spill_count: 0
    .symbol:         _Z9hymba_fwd6Params.kd
    .uniform_work_group_size: 1
    .uses_dynamic_stack: false
    .vgpr_count:     248
    .vgpr_spill_count: 0
    .wavefront_size: 64
